# attention phase: one static s_setprio 1 for waves 4-7 (reset to 0 at phase end), on top of the previous best
# speedup vs baseline: 1.0015x; 1.0015x over previous
.LBB0_441:
	s_load_dwordx2 s[28:29], s[10:11], 0xd8
	s_load_dwordx2 s[40:41], s[10:11], 0xa8
	s_waitcnt lgkmcnt(0)
	s_add_u32 s42, s28, 0x14400000
	s_addc_u32 s43, s29, 0
	s_add_u32 s26, s28, 0x15000000
	s_addc_u32 s34, s29, 0
	s_add_u32 s35, s28, 0x15700000
	s_addc_u32 s48, s29, 0
	s_lshl_b32 s49, s12, 2
	s_add_u32 s44, s28, 0xfb00000
	s_addc_u32 s45, s29, 0
	s_add_u32 s56, s28, 0x11300000
	s_addc_u32 s57, s29, 0
	s_add_u32 s46, s28, 0x14200000
	s_addc_u32 s47, s29, 0
	v_readfirstlane_b32 s10, v240
	s_cmpk_lt_u32 s10, 0x100
	s_cbranch_scc1 .Lattn_prio_done
	s_setprio 1
.Lattn_prio_done:
	s_branch .LBB0_445

.LBB0_511:
	s_setprio 0
	s_add_i32 s5, s97, 5
	s_cmp_ge_i32 s5, s27
	s_waitcnt vmcnt(0)
	s_barrier
	s_cbranch_scc1 .LBB0_565
	s_waitcnt vmcnt(0)
	v_mov_b32_e32 v0, v240
	s_barrier
	s_nop 0
	v_cmp_eq_u32_e32 vcc, 0, v0
	s_and_saveexec_b64 s[14:15], vcc
	s_cbranch_execz .LBB0_564
	v_readlane_b32 s10, v254, 48
	s_waitcnt vmcnt(0) expcnt(0) lgkmcnt(0)
	s_nop 0
	v_mov_b32_e32 v0, s10
	ds_read_b32 v3, v0
	v_readlane_b32 s10, v254, 49
	s_waitcnt lgkmcnt(0)
	v_cmp_ne_u32_e32 vcc, 0, v3
	v_mov_b32_e32 v0, s10
	ds_read_b32 v2, v0
	s_cbranch_vccnz .LBB0_528
	s_mov_b32 s13, s54
	s_mov_b32 s24, 1
	s_branch .LBB0_516
